# final grid barrier replaced: 248 non-GEMM workgroups exit after the prompt final-norm; the 8 sample-tile workgroups sync among themselves (8-way counter) and normalise the 512 sample rows
# speedup vs baseline: 1.0074x; 1.0056x over previous
.LBB0_695:
	s_waitcnt vmcnt(0) lgkmcnt(0)
	s_waitcnt vmcnt(0) lgkmcnt(0)
	s_barrier
	s_load_dword s6, s[84:85], 0x0
	s_waitcnt lgkmcnt(0)
	s_cmp_lt_u32 s6, 9
	s_cbranch_scc1 .Lfb_orig
	s_cmp_gt_u32 s93, 7
	s_cbranch_scc0 .Lfb_small
	s_endpgm
.Lfb_small:
	v_cmp_eq_u32_e32 vcc, 0, v197
	s_and_saveexec_b64 s[0:1], vcc
	s_cbranch_execz .Lfb_join
	buffer_wbl2 sc1
	s_waitcnt vmcnt(0)
	v_mov_b32_e32 v0, 0
	v_mov_b32_e32 v1, 1
	global_atomic_add v0, v1, s[10:11] offset:512
.Lfb_poll:
	global_load_dword v1, v0, s[10:11] offset:512 sc1
	s_waitcnt vmcnt(0)
	v_cmp_gt_u32_e32 vcc, 8, v1
	s_cbranch_vccz .Lfb_done
	s_sleep 4
	s_branch .Lfb_poll

.Lfb_join:
	s_or_b64 exec, exec, s[0:1]
	v_mov_b32_e32 v16, 8
	v_readlane_b32 s36, v254, 56
	v_readlane_b32 s37, v254, 57
	v_readlane_b32 s38, v254, 58
	v_readlane_b32 s39, v254, 59
	v_readlane_b32 s40, v254, 60
	v_readlane_b32 s41, v254, 61
	v_readlane_b32 s42, v254, 62
	v_readlane_b32 s43, v254, 63
	s_mov_b64 s[28:29], s[40:41]
	s_mov_b64 s[30:31], s[42:43]
	s_barrier
	s_branch .Lfb_final
.Lfb_orig:
	s_load_dword s6, s[84:85], 0x0
	v_cmp_eq_u32_e32 vcc, 0, v197
	s_waitcnt lgkmcnt(0)
	v_mov_b32_e32 v16, s6
	s_and_saveexec_b64 s[0:1], vcc
	v_readlane_b32 s36, v254, 56
	v_readlane_b32 s40, v254, 60
	v_readlane_b32 s41, v254, 61
	v_readlane_b32 s42, v254, 62
	v_readlane_b32 s43, v254, 63
	s_mov_b64 s[28:29], s[40:41]
	s_mov_b64 s[30:31], s[42:43]
	v_readlane_b32 s37, v254, 57
	v_readlane_b32 s38, v254, 58
	v_readlane_b32 s39, v254, 59
	s_cbranch_execz .LBB0_704
	s_mov_b64 s[2:3], exec
	buffer_wbl2 sc1
	s_waitcnt vmcnt(0)
	v_mbcnt_lo_u32_b32 v0, s2, 0
	v_mbcnt_hi_u32_b32 v0, s3, v0
	v_cmp_eq_u32_e32 vcc, 0, v0
	s_and_saveexec_b64 s[4:5], vcc
	s_cbranch_execz .LBB0_698
	s_bcnt1_i32_b64 s2, s[2:3]
	v_mov_b32_e32 v2, s2
	v_readlane_b32 s2, v254, 34
	v_mov_b32_e32 v1, 0
	v_readlane_b32 s3, v254, 35
	s_nop 4
	global_atomic_add v1, v1, v2, s[2:3] sc0

.Lfb_final:
	v_readlane_b32 s1, v254, 0
	v_readfirstlane_b32 s0, v197
	s_ashr_i32 s0, s0, 6
	s_add_i32 s0, s1, s0
	s_addk_i32 s0, 0x4000
	s_cmpk_gt_i32 s0, 0x407f
	s_movk_i32 s17, 0x407f
	s_cbranch_scc1 .LBB0_707
	v_lshlrev_b32_e32 v0, 4, v197
	v_and_b32_e32 v17, 0x3f0, v0
	global_load_dwordx4 v[0:3], v17, s[28:29]
	global_load_dwordx4 v[4:7], v17, s[28:29] offset:1024
	global_load_dwordx4 v[8:11], v17, s[28:29] offset:2048
	global_load_dwordx4 v[12:15], v17, s[28:29] offset:3072
	s_ashr_i32 s1, s0, 31
	s_lshl_b64 s[2:3], s[0:1], 14
	v_and_b32_e32 v22, 63, v197
	s_add_u32 s2, s30, s2
	v_lshlrev_b32_e32 v16, 3, v16
	v_lshlrev_b32_e32 v18, 4, v22
	v_mov_b32_e32 v19, 0
	s_addc_u32 s3, s31, s3
	v_lshl_add_u64 v[18:19], s[2:3], 0, v[18:19]
	v_ashrrev_i32_e32 v17, 31, v16
	s_lshl_b64 s[2:3], s[0:1], 13
	v_lshlrev_b64 v[20:21], 14, v[16:17]
	v_lshl_or_b32 v22, v22, 3, s2
	v_mov_b32_e32 v23, s3
	v_lshlrev_b64 v[24:25], 13, v[16:17]
	s_lshl_b64 s[2:3], s[0:1], 8
	v_lshlrev_b64 v[26:27], 8, v[16:17]
	v_mov_b32_e32 v17, s0
	s_mov_b32 s0, 0x358637bd
	v_readlane_b32 s24, v254, 50
	s_mov_b64 s[6:7], 0
	v_mov_b64_e32 v[28:29], s[2:3]
	s_mov_b64 s[8:9], 0x3c1d8000
	s_mov_b64 s[10:11], 0x3c1d8040
	s_mov_b64 s[12:13], 0x3c1d8080
	s_mov_b32 s18, 0x101000
	s_mov_b64 s[14:15], 0x3c1d80c0
	s_mov_b32 s16, 0x3a800000
	v_mov_b64_e32 v[30:31], s[0:1]
	s_mov_b32 s19, 0x800000
	s_movk_i32 s20, 0x1000
	s_movk_i32 s21, 0x2000
	s_movk_i32 s22, 0x3000
	v_readlane_b32 s25, v254, 51
	v_readlane_b32 s26, v254, 52
	v_readlane_b32 s27, v254, 53
